# next-tile operand prefetch: gemm_in and FF1 issue the next tile's first 8 LDS-DMA loads before the epilogue stores (FF1 with counted prologue waits)
# baseline (speedup 1.0000x reference)
; DI int bidx() { int b = blockIdx.x; asm volatile("" : "+s"(b)); return b; }
; DI void phase0a(const Params& p, char* lds) {
;     ...
;   for (int it = bidx(); it < NITEMS; it += gridDim.x) {
;     if (it < N_SSM) { ssm_tables(p, it >> 1, it & 1, lds); continue; }
;     int i = it - N_SSM;
;     if (i < N_MOD) { mod_item(p, i, lds); continue; }
;     i -= N_MOD;
;     if (i < N_ROPE) {
;       float2* rope = (float2*)(p.ws + OFF_ROPE);
;       for (int e = tid; e < 4096; e += NT) {
;         const int pos = i * 512 + (e >> 3), f = e & 7;
;         const double invf = exp2(-(double)f * 0.125 * 18.931568569324174);
;         float s, c; sincos_rev((double)pos * invf, s, c);
;         rope[pos * 8 + f] = make_float2(c, s);
;       }
; __global__ void __launch_bounds__(NT) fwd_megakernel(Params p) {
;   __shared__ __attribute__((aligned(16))) char lds[LDS_BYTES];
;   cg::grid_group grid = cg::this_grid();
;   phase0a(p, lds);
_Z14fwd_megakernel6Params:
	s_add_u32 s4, s0, 0x130
	s_addc_u32 s5, s1, 0
	v_and_b32_e32 v162, 0x3ff, v0
	v_writelane_b32 v254, s4, 0
	v_mov_b32_e32 v1, v162
	s_mov_b32 s74, s2
	v_writelane_b32 v254, s5, 1
	v_writelane_b32 v254, s0, 2
	s_load_dword s12, s[0:1], 0x130
	s_cmpk_gt_i32 s74, 0x11a0
	v_writelane_b32 v254, s1, 3
	v_writelane_b32 v254, s2, 4
	s_waitcnt lgkmcnt(0)
	s_mov_b32 s20, 0
	v_writelane_b32 v255, s20, 51
	v_writelane_b32 v254, s12, 5
	s_cbranch_scc1 .LBB0_91
	s_movk_i32 s0, 0x1000
	v_and_b32_e32 v58, 7, v1
	v_cmp_gt_i32_e64 s[4:5], s0, v1
	v_cvt_f64_u32_e32 v[2:3], v58
	s_mov_b32 s0, 0x471b3a95
	v_ldexp_f64 v[2:3], -v[2:3], -3
	s_mov_b32 s1, 0x4032ee7b
	v_mul_f64 v[20:21], v[2:3], s[0:1]
	v_rndne_f64_e32 v[22:23], v[20:21]
	v_add_f64 v[2:3], v[20:21], -v[22:23]
	s_mov_b32 s45, 0x3c7abc9e
	s_mov_b32 s44, 0x3b39803f
	v_mul_f64 v[24:25], v[2:3], s[44:45]
	s_mov_b32 s47, 0x3fe62e42
	s_mov_b32 s46, 0xfefa39ef
	v_fmac_f64_e32 v[24:25], s[46:47], v[2:3]
	v_mov_b32_e32 v2, 0xfca7ab0c
	v_mov_b32_e32 v3, 0x3e928af3
	s_mov_b32 s48, 0x6a5dcb37
	s_mov_b32 s49, 0x3e5ade15
	v_mov_b64_e32 v[6:7], v[2:3]
	v_mov_b32_e32 v4, 0x623fde64
	v_mov_b32_e32 v5, 0x3ec71dee
	v_fmac_f64_e32 v[6:7], s[48:49], v[24:25]
	v_mov_b64_e32 v[8:9], v[4:5]
	v_fmac_f64_e32 v[8:9], v[24:25], v[6:7]
	v_mov_b32_e32 v6, 0x7c89e6b0
	v_mov_b32_e32 v7, 0x3efa0199
	v_mov_b64_e32 v[10:11], v[6:7]
	v_fmac_f64_e32 v[10:11], v[24:25], v[8:9]
	v_mov_b32_e32 v8, 0x14761f6e
	v_mov_b32_e32 v9, 0x3f2a01a0
	v_mov_b64_e32 v[12:13], v[8:9]
	v_fmac_f64_e32 v[12:13], v[24:25], v[10:11]
	v_mov_b32_e32 v10, 0x1852b7b0
	v_mov_b32_e32 v11, 0x3f56c16c
	v_mov_b64_e32 v[14:15], v[10:11]
	v_fmac_f64_e32 v[14:15], v[24:25], v[12:13]
	v_mov_b32_e32 v12, 0x11122322
	v_mov_b32_e32 v13, 0x3f811111
	v_mov_b64_e32 v[16:17], v[12:13]
	v_fmac_f64_e32 v[16:17], v[24:25], v[14:15]
	v_mov_b32_e32 v14, 0x555502a1
	v_mov_b32_e32 v15, 0x3fa55555
	v_mov_b64_e32 v[18:19], v[14:15]
	v_fmac_f64_e32 v[18:19], v[24:25], v[16:17]
	v_mov_b32_e32 v16, 0x55555511
	v_mov_b32_e32 v17, 0x3fc55555
	v_mov_b64_e32 v[26:27], v[16:17]
	v_fmac_f64_e32 v[26:27], v[24:25], v[18:19]
	v_mov_b32_e32 v18, 11
	v_mov_b32_e32 v19, 0x3fe00000
	v_readlane_b32 s2, v254, 2
	v_mov_b64_e32 v[28:29], v[18:19]
	v_readlane_b32 s3, v254, 3
	v_fmac_f64_e32 v[28:29], v[24:25], v[26:27]
	s_load_dwordx2 s[54:55], s[2:3], 0x128
	s_load_dwordx2 s[0:1], s[2:3], 0x118
	v_fma_f64 v[26:27], v[24:25], v[28:29], 1.0
	s_mov_b32 s50, 0
	s_mov_b32 s52, 0
	v_fma_f64 v[24:25], v[24:25], v[26:27], 1.0
	v_cvt_i32_f64_e32 v22, v[22:23]
	s_mov_b32 s51, 0x40900000
	s_mov_b32 s53, 0xc090cc00
	v_ldexp_f64 v[22:23], v[24:25], v22
	v_mov_b32_e32 v59, 0x7ff00000
	v_cmp_nlt_f64_e32 vcc, s[50:51], v[20:21]
	v_cmp_ngt_f64_e64 s[8:9], s[52:53], v[20:21]
	s_waitcnt lgkmcnt(0)
	v_writelane_b32 v254, s0, 6
	v_cndmask_b32_e32 v23, v59, v23, vcc
	s_and_b64 vcc, s[8:9], vcc
	s_add_u32 s33, s54, 0x1880000
	v_writelane_b32 v254, s1, 7
	s_addc_u32 s0, s55, 0
	v_writelane_b32 v254, s0, 8
	s_add_u32 s0, s54, 0x1080000
	v_writelane_b32 v254, s0, 9
	s_addc_u32 s0, s55, 0
	v_writelane_b32 v254, s0, 10
	s_add_u32 s0, s54, 0xe80000
	v_writelane_b32 v254, s0, 11
	s_addc_u32 s0, s55, 0
	v_writelane_b32 v254, s0, 12
	s_load_dwordx2 s[0:1], s[2:3], 0xe8
	s_load_dwordx2 s[92:93], s[2:3], 0x70
	s_load_dwordx4 s[28:31], s[2:3], 0xd0
	s_load_dwordx8 s[20:27], s[2:3], 0xf8
	s_mov_b32 s66, 0x6dc9c883
	s_mov_b32 s68, 0x652b82fe
	s_mov_b32 s6, 0x54442d18
	s_waitcnt lgkmcnt(0)
	v_writelane_b32 v254, s0, 14
	s_mov_b32 s60, 0x33145c00
	s_mov_b32 s88, 0x46cc5e42
	v_writelane_b32 v254, s1, 15
	s_add_u32 s0, s54, 0xe00000
	v_writelane_b32 v254, s0, 16
	s_addc_u32 s0, s55, 0
	v_writelane_b32 v254, s0, 18
	s_add_u32 s0, s54, 0xd00000
	v_writelane_b32 v254, s0, 19
	s_addc_u32 s0, s55, 0
	v_writelane_b32 v254, s0, 20
	s_add_u32 s0, s54, 0xb00000
	v_writelane_b32 v254, s0, 22
	s_addc_u32 s0, s55, 0
	v_writelane_b32 v254, s0, 24
	v_writelane_b32 v254, s20, 26
	s_add_u32 s86, s54, 0x43a4000
	s_addc_u32 s87, s55, 0
	v_writelane_b32 v254, s21, 27
	v_writelane_b32 v254, s22, 28
	v_writelane_b32 v254, s23, 29
	s_add_u32 s62, s54, 0x42a4000
	v_writelane_b32 v254, s24, 30
	s_addc_u32 s63, s55, 0
	v_writelane_b32 v254, s25, 31
	s_add_u32 s64, s54, 0x4280000
	v_writelane_b32 v254, s26, 32
	s_addc_u32 s65, s55, 0
	v_writelane_b32 v254, s27, 33
	s_load_dwordx8 s[20:27], s[2:3], 0x50
	s_load_dwordx8 s[36:43], s[2:3], 0x10
	s_add_u32 s12, s54, 0x4080000
	s_addc_u32 s13, s55, 0
	s_add_u32 s14, s54, 0x2080000
	s_mul_i32 s0, s74, 24
	s_mov_b32 s90, 0x55555555
	s_mov_b32 s80, 0xf9a43bb8
	s_mov_b32 s35, 0
	v_cmp_eq_u32_e64 s[84:85], 0, v1
	v_cndmask_b32_e64 v21, 0, v23, s[8:9]
	v_cndmask_b32_e32 v20, 0, v22, vcc
	s_addc_u32 s15, s55, 0
	s_add_i32 s34, s0, 0xfffffa00
	v_mov_b32_e32 v23, 0
	s_movk_i32 s17, 0x5800
	s_mov_b32 s67, 0x3fc45f30
	s_movk_i32 s59, 0x1800
	s_movk_i32 s18, 0x400
	s_movk_i32 s19, 0x6000
	s_mov_b32 s69, 0x3ff71547
	s_mov_b32 s47, 0xbfe62e42
	s_mov_b32 s45, 0xbc7abc9e
	s_mov_b32 s7, 0xbff921fb
	s_mov_b32 s61, 0xbc91a626
	s_mov_b32 s89, 0xbda907db
	s_mov_b32 s91, 0xbfc55555
	s_mov_b32 s81, 0x3de5e0b2
	s_brev_b32 s58, 1
	s_movk_i32 s16, 0x7dff
	v_mov_b32_e32 v60, 0x7f800000
	v_mov_b32_e32 v61, 0x40100000
	v_mov_b32_e32 v62, 0x3ff00000
	v_mov_b32_e32 v24, 0x9037ab78
	v_mov_b32_e32 v25, 0x3e21eeb6
	v_mov_b32_e32 v26, 0xa17f65f6
	v_mov_b32_e32 v27, 0xbe927e4f
	v_mov_b32_e32 v28, 0x19f4ec90
	v_mov_b32_e32 v29, 0x3efa01a0
	v_mov_b32_e32 v30, 0x16c16967
	v_mov_b32_e32 v31, 0xbf56c16c
	v_mov_b32_e32 v32, 0x55555555
	v_mov_b32_e32 v34, 0xb42fdfa7
	v_mov_b32_e32 v35, 0xbe5ae600
	v_mov_b32_e32 v36, 0x796cde01
	v_mov_b32_e32 v37, 0x3ec71de3
	v_mov_b32_e32 v38, 0x19e83e5c
	v_mov_b32_e32 v39, 0xbf2a01a0
	v_mov_b32_e32 v40, 0x11110bb3
	v_mov_b32_e32 v63, 0x7ff80000
	v_mov_b32_e32 v64, 0x4200
	s_mov_b64 s[82:83], 0x180000
	s_mov_b32 s71, 0x3ff921fb
	s_mov_b32 s73, 0x3c91a626
	s_mov_b32 s78, 0x33145c07
	s_mov_b32 s77, 0x3fe45f30
	s_branch .LBB0_4

; DI int bidx() { int b = blockIdx.x; asm volatile("" : "+s"(b)); return b; }
; #define P8WV(n) asm volatile("s_waitcnt vmcnt(" #n ")" ::: "memory")
; #define P8BAR __builtin_amdgcn_s_barrier()
;     ...
;   P8STAGE_B(P8SB(0, 0), 0, 0); P8STAGE_A(P8SA(0, 0), 0, 0);
;   P8STAGE_B(P8SB(0, 1), 1, 0); P8STAGE_A(P8SA(0, 1), 1, 0);
;   if (wr == 1) P8BAR;
;   P8WV(4); P8BAR;
;   P8STAGE_B(P8SB(1, 0), 0, 1); P8STAGE_A(P8SA(1, 0), 0, 1); P8STAGE_B(P8SB(1, 1), 1, 1);
;   P8WV(6); P8BAR;
; DI void phase_gemm_in(const Params& p, int hf, char* lds) {
;     ...
;   for (int it = bidx(); it < 128 * NTN; it += gridDim.x) {
;     const int mt = it / NTN, nt = it % NTN;
;     acc8_t acc;
; #pragma unroll
;     for (int a = 0; a < 2; ++a)
; #pragma unroll
;       for (int b = 0; b < 2; ++b)
; #pragma unroll
;         for (int m = 0; m < 4; ++m)
; #pragma unroll
;           for (int q = 0; q < 2; ++q) acc[a][b][m][q] = f32x4v{0.f, 0.f, 0.f, 0.f};
;     asm volatile("s_waitcnt vmcnt(0)" ::: "memory");
;     gemm_main8(acc, W + (size_t)nt * 256 * 1024, 1024, h1 + (size_t)mt * 256 * 1024, 1024, 16, lds);
.LBB0_137:
	v_mov_b32_e32 v3, v162
	s_waitcnt vmcnt(0)
	s_mul_hi_i32 s0, s21, 0x2e8ba2e9
	v_ashrrev_i32_e32 v0, 31, v3
	v_lshrrev_b32_e32 v0, 26, v0
	v_add_u32_e32 v0, v3, v0
	v_ashrrev_i32_e32 v2, 6, v0
	v_bfe_i32 v0, v3, 27, 1
	v_lshlrev_b32_e32 v134, 4, v3
	v_lshrrev_b32_e32 v0, 22, v0
	v_add_u32_e32 v0, v134, v0
	v_and_b32_e32 v0, 0xfffffc00, v0
	v_sub_u32_e32 v0, v134, v0
	s_lshr_b32 s1, s0, 31
	s_ashr_i32 s0, s0, 2
	v_lshrrev_b32_e32 v1, 4, v0
	s_add_i32 s4, s0, s1
	v_bitop3_b32 v1, v1, v0, 32 bitop3:0x6c
	v_ashrrev_i32_e32 v0, 31, v0
	s_mul_i32 s0, s4, 22
	v_lshrrev_b32_e32 v0, 26, v0
	s_sub_i32 s8, s21, s0
	v_lshlrev_b32_e32 v4, 3, v2
	v_add_u32_e32 v0, v1, v0
	s_ashr_i32 s9, s8, 31
	v_and_b32_e32 v6, 0x1ffff0, v4
	v_ashrrev_i32_e32 v4, 6, v0
	s_lshl_b64 s[0:1], s[8:9], 19
	v_mul_i32_i24_e32 v5, 64, v4
	s_add_u32 s24, s10, s0
	v_sub_u32_e32 v1, v1, v5
	s_addc_u32 s25, s11, s1
	s_ashr_i32 s5, s4, 31
	v_lshlrev_b32_e32 v0, 5, v2
	v_ashrrev_i16_sdwa v1, v175, sext(v1) dst_sel:DWORD dst_unused:UNUSED_PAD src0_sel:DWORD src1_sel:BYTE_0
	s_lshl_b64 s[80:81], s[4:5], 19
	v_and_b32_e32 v0, 32, v0
	v_bfe_i32 v5, v1, 0, 16
	v_add_u32_e32 v136, 0x10000, v134
	s_add_u32 s0, s26, s80
	v_add_u32_e32 v0, v0, v5
	v_add_lshl_u32 v1, v4, v6, 11
	v_readlane_b32 vcc_lo, v255, 51
	s_nop 4
	s_mov_b32 vcc_hi, 0
	s_mov_b64 vcc, vcc
	v_readfirstlane_b32 s5, v136
	s_addc_u32 s1, s27, s81
	v_lshl_add_u32 v152, v0, 1, v1
	s_mov_b32 m0, s5
	v_add_u32_e32 v138, 0x12000, v134
	v_lshl_add_u64 v[0:1], s[0:1], 0, v[152:153]
	s_cbranch_vccnz .Lpfgin_s0
	global_load_lds_dwordx4 v152, s[0:1]
.Lpfgin_s0:
	v_readfirstlane_b32 s0, v138
	v_lshl_add_u64 v[6:7], v[0:1], 0, s[44:45]
	s_mov_b32 m0, s0
	v_readfirstlane_b32 s0, v134
	v_add_u32_e32 v139, 0x2000, v134
	s_cbranch_vccnz .Lpfgin_s1
	global_load_lds_dwordx4 v[6:7], off
.Lpfgin_s1:
	v_lshl_add_u64 v[128:129], s[24:25], 0, v[152:153]
	s_mov_b32 m0, s0
	v_readfirstlane_b32 s0, v139
	v_add_u32_e32 v140, 0x14000, v134
	s_cbranch_vccnz .Lpfgin_s2
	global_load_lds_dwordx4 v152, s[24:25]
.Lpfgin_s2:
	v_lshl_add_u64 v[6:7], v[128:129], 0, s[44:45]
	s_mov_b32 m0, s0
	v_readfirstlane_b32 s0, v140
	v_add_u32_e32 v141, 0x16000, v134
	s_cbranch_vccnz .Lpfgin_s3
	global_load_lds_dwordx4 v[6:7], off
.Lpfgin_s3:
	v_lshl_add_u64 v[6:7], v[0:1], 0, s[50:51]
	s_mov_b32 m0, s0
	v_readfirstlane_b32 s0, v141
	v_add_u32_e32 v142, 0x4000, v134
	s_cbranch_vccnz .Lpfgin_s4
	global_load_lds_dwordx4 v[6:7], off
.Lpfgin_s4:
	v_lshl_add_u64 v[6:7], v[0:1], 0, s[64:65]
	s_mov_b32 m0, s0
	v_readfirstlane_b32 s0, v142
	v_add_u32_e32 v143, 0x6000, v134
	s_cbranch_vccnz .Lpfgin_s5
	global_load_lds_dwordx4 v[6:7], off
.Lpfgin_s5:
	v_lshl_add_u64 v[6:7], v[128:129], 0, s[50:51]
	s_mov_b32 m0, s0
	v_readfirstlane_b32 s0, v143
	s_cbranch_vccnz .Lpfgin_s6
	global_load_lds_dwordx4 v[6:7], off
.Lpfgin_s6:
	v_lshl_add_u64 v[6:7], v[128:129], 0, s[64:65]
	s_mov_b32 m0, s0
	v_readfirstlane_b32 s0, v3
	s_cbranch_vccnz .Lpfgin_s7
	global_load_lds_dwordx4 v[6:7], off
.Lpfgin_s7:
	s_ashr_i32 s1, s0, 8
	s_cmp_lg_u32 s1, 1
	s_cbranch_scc1 .LBB0_139
	s_barrier

; DI int tidx() { int t = threadIdx.x; asm volatile("" : "+v"(t)); return t; }
;     ...
;   P8STAGE_B(P8SB(0, 0), 0, 0); P8STAGE_A(P8SA(0, 0), 0, 0);
;   P8STAGE_B(P8SB(0, 1), 1, 0); P8STAGE_A(P8SA(0, 1), 1, 0);
; DI void phase_gemm_in(const Params& p, int hf, char* lds) {
;     ...
;     gemm_main8(acc, W + (size_t)nt * 256 * 1024, 1024, h1 + (size_t)mt * 256 * 1024, 1024, 16, lds);
;     const int lane = tidx() & 63, wid = tidx() >> 6, wr = wid >> 2, wc = wid & 3, fr = lane & 15, fq = lane >> 4;
;     const int m0 = mt * 256;
;     ...
;     if (nt < 8) {
;       const bool isq = nt < 4;
;       unsigned char* dst8 = (unsigned char*)(p.ws + OFF_K) + (isq ? OFF_Q8 : 0) + (nt & 3) * 256;
;       const float qs = isq ? 0.125f * 1.44269504089f : 1.0f;
; #pragma unroll
;       for (int bj = 0; bj < 2; ++bj)
; #pragma unroll
;         for (int q = 0; q < 2; ++q) {
;           const int pos = (m0 + bj * 128 + wc * 32 + q * 16 + fr) & lmask;
.LBB0_143:
	s_add_i32 s56, s21, s16
	s_mov_b32 s57, 0
	s_cmpk_lt_i32 s56, 0xb00
	s_cbranch_scc0 .Lpfgin_none
	s_mul_hi_u32 s57, s56, 0x2e8ba2e9
	s_lshr_b32 s57, s57, 2
	s_mul_i32 s80, s57, 22
	s_sub_i32 s56, s56, s80
	s_lshl_b32 s56, s56, 19
	s_lshl_b32 s57, s57, 19
	s_add_u32 s24, s10, s56
	s_addc_u32 s25, s11, 0
	s_add_u32 s80, s26, s57
	s_addc_u32 s81, s27, 0
	v_readfirstlane_b32 s56, v162
	s_nop 3
	s_lshl_b32 s56, s56, 4
	v_lshl_add_u64 v[182:183], s[80:81], 0, v[152:153]
	v_lshl_add_u64 v[184:185], s[24:25], 0, v[152:153]
	s_add_i32 m0, s56, 0x10000
	s_nop 0
	global_load_lds_dwordx4 v152, s[80:81]
	s_add_i32 m0, s56, 0x12000
	v_lshl_add_u64 v[186:187], v[182:183], 0, s[44:45]
	global_load_lds_dwordx4 v[186:187], off
	s_mov_b32 m0, s56
	s_nop 0
	global_load_lds_dwordx4 v152, s[24:25]
	s_add_i32 m0, s56, 0x2000
	v_lshl_add_u64 v[186:187], v[184:185], 0, s[44:45]
	global_load_lds_dwordx4 v[186:187], off
	s_add_i32 m0, s56, 0x14000
	v_lshl_add_u64 v[186:187], v[182:183], 0, s[50:51]
	global_load_lds_dwordx4 v[186:187], off
	s_add_i32 m0, s56, 0x16000
	v_lshl_add_u64 v[186:187], v[182:183], 0, s[64:65]
	global_load_lds_dwordx4 v[186:187], off
	s_add_i32 m0, s56, 0x4000
	v_lshl_add_u64 v[186:187], v[184:185], 0, s[50:51]
	global_load_lds_dwordx4 v[186:187], off
	s_add_i32 m0, s56, 0x6000
	v_lshl_add_u64 v[186:187], v[184:185], 0, s[64:65]
	global_load_lds_dwordx4 v[186:187], off
	s_mov_b32 s57, 1
.Lpfgin_none:
	v_writelane_b32 v255, s57, 51
	v_mov_b32_e32 v146, v162
	v_mov_b32_e32 v128, v162
	s_lshl_b32 s9, s4, 8
	v_bfe_u32 v144, v146, 4, 2
	v_ashrrev_i32_e32 v130, 8, v128
	v_bfe_u32 v145, v128, 6, 2
	v_lshlrev_b32_e32 v128, 2, v144
	v_and_b32_e32 v131, 15, v146
	s_mov_b64 s[4:5], -1
	s_cmp_gt_i32 s8, 7
	v_lshl_or_b32 v128, v130, 6, v128
	s_cbranch_scc1 .LBB0_145
	s_andn2_b64 vcc, exec, s[4:5]
	s_cbranch_vccnz .LBB0_136
	s_branch .LBB0_154

; DI int tidx() { int t = threadIdx.x; asm volatile("" : "+v"(t)); return t; }
; template <bool RELU2>
; DI void phase_gemm_plain(const bf16_t* X, int K, const bf16_t* W, int N, bf16_t* out, char* lds) {
;     ...
;     const int lane = tidx() & 63, wid = tidx() >> 6, wr = wid >> 2, wc = wid & 3, fr = lane & 15, fq = lane >> 4;
; #pragma unroll
;     for (int ai = 0; ai < 2; ++ai)
; #pragma unroll
;       for (int bj = 0; bj < 2; ++bj)
; #pragma unroll
;         for (int m = 0; m < 4; ++m)
; #pragma unroll
;           for (int q = 0; q < 2; ++q) {
;             float a = acc[ai][bj][m][q][0], b = acc[ai][bj][m][q][1], c = acc[ai][bj][m][q][2], d = acc[ai][bj][m][q][3];
;             if (RELU2) { a = fmaxf(a, 0.f); a *= a; b = fmaxf(b, 0.f); b *= b; c = fmaxf(c, 0.f); c *= c; d = fmaxf(d, 0.f); d *= d; }
;             const int tok = mt * 256 + bj * 128 + wc * 32 + q * 16 + fr, n = nt * 256 + ai * 128 + wr * 64 + m * 16 + fq * 4;
;             store_bf4(out + (size_t)tok * N + n, a, b, c, d);
;           }
.LBB0_349:
	v_and_b32_e32 v190, 15, v162
	v_bfe_u32 v191, v162, 6, 2
	v_lshl_or_b32 v190, v191, 5, v190
	v_mul_u32_u24_e32 v190, 0x210, v190
	v_lshrrev_b32_e32 v191, 8, v162
	v_bfe_u32 v192, v162, 4, 2
	v_lshlrev_b32_e32 v191, 7, v191
	v_lshl_or_b32 v191, v192, 3, v191
	v_add_u32_e32 v190, v190, v191
	v_add_u32_e32 v191, 0x2100, v190
	v_add_u32_e32 v192, 0x10800, v190
	v_add_u32_e32 v193, 0x12900, v190
	v_lshrrev_b32_e32 v194, 6, v162
	v_bfe_u32 v195, v162, 5, 1
	v_lshl_or_b32 v194, v194, 5, v195
	v_and_b32_e32 v195, 31, v162
	v_lshlrev_b32_e32 v195, 4, v195
	s_lshl_b32 s12, s80, 8
	v_add_u32_e32 v196, s12, v194
	v_lshlrev_b32_e32 v196, 13, v196
	s_lshl_b32 s12, s8, 9
	v_add3_u32 v196, v196, s12, v195
	v_mov_b32_e32 v197, 0
	v_readlane_b32 s82, v254, 22
	v_readlane_b32 s83, v254, 23
	v_mul_u32_u24_e32 v194, 0x210, v194
	v_add_u32_e32 v194, v194, v195
	s_mov_b32 s24, 0x4000
	s_mov_b32 s25, 0
	s_nop 1
	v_lshl_add_u64 v[196:197], s[82:83], 0, v[196:197]
	v_max_f32_e32 v124, v124, v124
	v_max_f32_e32 v125, v125, v125
	v_max_f32_e32 v124, 0, v124
	v_max_f32_e32 v125, 0, v125
	v_mov_b32_e32 v129, v162
	v_mov_b32_e32 v130, v162
	v_pk_mul_f32 v[132:133], v[124:125], v[124:125]
	v_max_f32_e32 v124, v126, v126
	v_max_f32_e32 v125, v127, v127
	v_max_f32_e32 v124, 0, v124
	v_lshrrev_b32_e32 v131, 1, v130
	v_max_f32_e32 v125, 0, v125
	v_max_f32_e32 v120, v120, v120
	v_max_f32_e32 v121, v121, v121
	v_and_b32_e32 v128, 15, v129
	s_lshl_b32 s1, s80, 8
	v_and_b32_e32 v131, 0x60, v131
	v_pk_mul_f32 v[126:127], v[124:125], v[124:125]
	v_max_f32_e32 v120, 0, v120
	v_max_f32_e32 v121, 0, v121
	v_or3_b32 v128, v131, s1, v128
	s_lshl_b32 s1, s8, 8
	v_ashrrev_i32_e32 v130, 2, v130
	v_lshrrev_b32_e32 v129, 2, v129
	v_cvt_pk_bf16_f32 v132, v132, v133
	v_cvt_pk_bf16_f32 v133, v126, v127
	v_pk_mul_f32 v[126:127], v[120:121], v[120:121]
	v_max_f32_e32 v120, v122, v122
	v_max_f32_e32 v121, v123, v123
	v_and_b32_e32 v130, 0xffffffc0, v130
	v_and_or_b32 v129, v129, 12, s1
	v_max_f32_e32 v120, 0, v120
	v_max_f32_e32 v121, 0, v121
	v_add_u32_e32 v130, v129, v130
	v_readlane_b32 s8, v254, 22
	v_pk_mul_f32 v[122:123], v[120:121], v[120:121]
	v_or_b32_e32 v120, 16, v128
	v_max_f32_e32 v96, v96, v96
	v_max_f32_e32 v97, v97, v97
	v_max_f32_e32 v98, v98, v98
	v_max_f32_e32 v99, v99, v99
	v_ashrrev_i32_e32 v131, 31, v130
	v_readlane_b32 s9, v254, 23
	v_ashrrev_i32_e32 v121, 31, v120
	v_max_f32_e32 v96, 0, v96
	v_max_f32_e32 v97, 0, v97
	v_max_f32_e32 v98, 0, v98
	v_max_f32_e32 v99, 0, v99
	v_max_f32_e32 v92, v92, v92
	v_max_f32_e32 v93, v93, v93
	v_lshl_add_u64 v[130:131], v[130:131], 1, s[8:9]
	v_lshlrev_b64 v[120:121], 13, v[120:121]
	v_pk_mul_f32 v[96:97], v[96:97], v[96:97]
	v_pk_mul_f32 v[98:99], v[98:99], v[98:99]
	v_max_f32_e32 v92, 0, v92
	v_max_f32_e32 v93, 0, v93
	v_lshl_add_u64 v[120:121], v[130:131], 0, v[120:121]
	v_cvt_pk_bf16_f32 v96, v96, v97
	v_cvt_pk_bf16_f32 v97, v98, v99
	v_pk_mul_f32 v[98:99], v[92:93], v[92:93]
	v_max_f32_e32 v92, v94, v94
	v_max_f32_e32 v93, v95, v95
	ds_write_b64 v191, v[96:97] offset:96
	v_or_b32_e32 v96, 0x80, v128
	v_max_f32_e32 v92, 0, v92
	v_max_f32_e32 v93, 0, v93
	v_max_f32_e32 v88, v88, v88
	v_max_f32_e32 v89, v89, v89
	v_pk_mul_f32 v[94:95], v[92:93], v[92:93]
	v_ashrrev_i32_e32 v97, 31, v96
	v_max_f32_e32 v88, 0, v88
	v_max_f32_e32 v89, 0, v89
	v_lshlrev_b64 v[92:93], 13, v[96:97]
	v_cvt_pk_bf16_f32 v97, v94, v95
	v_pk_mul_f32 v[94:95], v[88:89], v[88:89]
	v_max_f32_e32 v88, v90, v90
	v_max_f32_e32 v89, v91, v91
	v_max_f32_e32 v88, 0, v88
	v_max_f32_e32 v89, 0, v89
	v_max_f32_e32 v116, v116, v116
	v_max_f32_e32 v117, v117, v117
	v_max_f32_e32 v118, v118, v118
	v_max_f32_e32 v119, v119, v119
	v_max_f32_e32 v112, v112, v112
	v_max_f32_e32 v113, v113, v113
	v_max_f32_e32 v114, v114, v114
	v_max_f32_e32 v115, v115, v115
	v_max_f32_e32 v108, v108, v108
	v_max_f32_e32 v109, v109, v109
	v_max_f32_e32 v110, v110, v110
	v_max_f32_e32 v111, v111, v111
	v_max_f32_e32 v104, v104, v104
	v_max_f32_e32 v105, v105, v105
	v_max_f32_e32 v106, v106, v106
	v_max_f32_e32 v107, v107, v107
	v_max_f32_e32 v100, v100, v100
	v_max_f32_e32 v101, v101, v101
	v_max_f32_e32 v102, v102, v102
	v_max_f32_e32 v103, v103, v103
	v_pk_mul_f32 v[90:91], v[88:89], v[88:89]
	v_or_b32_e32 v88, 0x90, v128
	v_max_f32_e32 v84, v84, v84
	v_max_f32_e32 v85, v85, v85
	v_max_f32_e32 v86, v86, v86
	v_max_f32_e32 v87, v87, v87
	v_max_f32_e32 v80, v80, v80
	v_max_f32_e32 v81, v81, v81
	v_max_f32_e32 v82, v82, v82
	v_max_f32_e32 v83, v83, v83
	v_max_f32_e32 v76, v76, v76
	v_max_f32_e32 v77, v77, v77
	v_max_f32_e32 v78, v78, v78
	v_max_f32_e32 v79, v79, v79
	v_max_f32_e32 v72, v72, v72
	v_max_f32_e32 v73, v73, v73
	v_max_f32_e32 v74, v74, v74
	v_max_f32_e32 v75, v75, v75
	v_max_f32_e32 v68, v68, v68
	v_max_f32_e32 v69, v69, v69
	v_max_f32_e32 v70, v70, v70
	v_max_f32_e32 v71, v71, v71
	v_max_f32_e32 v64, v64, v64
	v_max_f32_e32 v65, v65, v65
	v_max_f32_e32 v66, v66, v66
	v_max_f32_e32 v67, v67, v67
	v_max_f32_e32 v60, v60, v60
	v_max_f32_e32 v61, v61, v61
	v_max_f32_e32 v62, v62, v62
	v_max_f32_e32 v63, v63, v63
	v_max_f32_e32 v56, v56, v56
	v_max_f32_e32 v57, v57, v57
	v_max_f32_e32 v58, v58, v58
	v_max_f32_e32 v59, v59, v59
	v_max_f32_e32 v52, v52, v52
	v_max_f32_e32 v53, v53, v53
	v_max_f32_e32 v54, v54, v54
	v_max_f32_e32 v55, v55, v55
	v_max_f32_e32 v48, v48, v48
	v_max_f32_e32 v49, v49, v49
	v_max_f32_e32 v50, v50, v50
	v_max_f32_e32 v51, v51, v51
	v_max_f32_e32 v44, v44, v44
	v_max_f32_e32 v45, v45, v45
	v_max_f32_e32 v46, v46, v46
	v_max_f32_e32 v47, v47, v47
	v_max_f32_e32 v40, v40, v40
	v_max_f32_e32 v41, v41, v41
	v_max_f32_e32 v42, v42, v42
	v_max_f32_e32 v43, v43, v43
; DI int tidx() { int t = threadIdx.x; asm volatile("" : "+v"(t)); return t; }
; template <bool RELU2>
; DI void phase_gemm_plain(const bf16_t* X, int K, const bf16_t* W, int N, bf16_t* out, char* lds) {
;     ...
;     const int lane = tidx() & 63, wid = tidx() >> 6, wr = wid >> 2, wc = wid & 3, fr = lane & 15, fq = lane >> 4;
; #pragma unroll
;     for (int ai = 0; ai < 2; ++ai)
; #pragma unroll
;       for (int bj = 0; bj < 2; ++bj)
; #pragma unroll
;         for (int m = 0; m < 4; ++m)
; #pragma unroll
;           for (int q = 0; q < 2; ++q) {
;             float a = acc[ai][bj][m][q][0], b = acc[ai][bj][m][q][1], c = acc[ai][bj][m][q][2], d = acc[ai][bj][m][q][3];
;             if (RELU2) { a = fmaxf(a, 0.f); a *= a; b = fmaxf(b, 0.f); b *= b; c = fmaxf(c, 0.f); c *= c; d = fmaxf(d, 0.f); d *= d; }
;             const int tok = mt * 256 + bj * 128 + wc * 32 + q * 16 + fr, n = nt * 256 + ai * 128 + wr * 64 + m * 16 + fq * 4;
;             store_bf4(out + (size_t)tok * N + n, a, b, c, d);
;           }
	v_max_f32_e32 v36, v36, v36
	v_max_f32_e32 v37, v37, v37
	v_max_f32_e32 v38, v38, v38
	v_max_f32_e32 v39, v39, v39
	v_max_f32_e32 v32, v32, v32
	v_max_f32_e32 v33, v33, v33
	v_max_f32_e32 v34, v34, v34
	v_max_f32_e32 v35, v35, v35
	v_max_f32_e32 v28, v28, v28
	v_max_f32_e32 v29, v29, v29
	v_max_f32_e32 v30, v30, v30
	v_max_f32_e32 v31, v31, v31
	v_max_f32_e32 v24, v24, v24
	v_max_f32_e32 v25, v25, v25
	v_max_f32_e32 v26, v26, v26
	v_max_f32_e32 v27, v27, v27
	v_max_f32_e32 v20, v20, v20
	v_max_f32_e32 v21, v21, v21
	v_max_f32_e32 v22, v22, v22
	v_max_f32_e32 v23, v23, v23
	v_max_f32_e32 v16, v16, v16
	v_max_f32_e32 v17, v17, v17
	v_max_f32_e32 v18, v18, v18
	v_max_f32_e32 v19, v19, v19
	v_max_f32_e32 v12, v12, v12
	v_max_f32_e32 v13, v13, v13
	v_max_f32_e32 v14, v14, v14
	v_max_f32_e32 v15, v15, v15
	v_max_f32_e32 v8, v8, v8
	v_max_f32_e32 v9, v9, v9
	v_max_f32_e32 v10, v10, v10
	v_max_f32_e32 v11, v11, v11
	v_max_f32_e32 v4, v4, v4
	v_max_f32_e32 v5, v5, v5
	v_max_f32_e32 v6, v6, v6
	v_max_f32_e32 v7, v7, v7
	v_max_f32_e32 v0, v0, v0
	v_max_f32_e32 v1, v1, v1
	v_max_f32_e32 v2, v2, v2
	v_max_f32_e32 v3, v3, v3
	v_ashrrev_i32_e32 v129, 31, v128
	v_max_f32_e32 v116, 0, v116
	v_max_f32_e32 v117, 0, v117
	v_max_f32_e32 v118, 0, v118
	v_max_f32_e32 v119, 0, v119
	v_max_f32_e32 v112, 0, v112
	v_max_f32_e32 v113, 0, v113
	v_max_f32_e32 v114, 0, v114
	v_max_f32_e32 v115, 0, v115
	v_max_f32_e32 v108, 0, v108
	v_max_f32_e32 v109, 0, v109
	v_max_f32_e32 v110, 0, v110
	v_max_f32_e32 v111, 0, v111
	v_max_f32_e32 v104, 0, v104
	v_max_f32_e32 v105, 0, v105
	v_max_f32_e32 v106, 0, v106
	v_max_f32_e32 v107, 0, v107
	v_max_f32_e32 v100, 0, v100
	v_max_f32_e32 v101, 0, v101
	v_max_f32_e32 v102, 0, v102
	v_max_f32_e32 v103, 0, v103
	v_ashrrev_i32_e32 v89, 31, v88
	v_max_f32_e32 v84, 0, v84
	v_max_f32_e32 v85, 0, v85
	v_max_f32_e32 v86, 0, v86
	v_max_f32_e32 v87, 0, v87
	v_max_f32_e32 v80, 0, v80
	v_max_f32_e32 v81, 0, v81
	v_max_f32_e32 v82, 0, v82
	v_max_f32_e32 v83, 0, v83
	v_max_f32_e32 v76, 0, v76
	v_max_f32_e32 v77, 0, v77
	v_max_f32_e32 v78, 0, v78
	v_max_f32_e32 v79, 0, v79
	v_max_f32_e32 v72, 0, v72
	v_max_f32_e32 v73, 0, v73
	v_max_f32_e32 v74, 0, v74
	v_max_f32_e32 v75, 0, v75
	v_max_f32_e32 v68, 0, v68
	v_max_f32_e32 v69, 0, v69
	v_max_f32_e32 v70, 0, v70
	v_max_f32_e32 v71, 0, v71
	v_max_f32_e32 v64, 0, v64
	v_max_f32_e32 v65, 0, v65
	v_max_f32_e32 v66, 0, v66
	v_max_f32_e32 v67, 0, v67
	v_max_f32_e32 v60, 0, v60
	v_max_f32_e32 v61, 0, v61
	v_max_f32_e32 v62, 0, v62
	v_max_f32_e32 v63, 0, v63
	v_max_f32_e32 v56, 0, v56
	v_max_f32_e32 v57, 0, v57
	v_max_f32_e32 v58, 0, v58
	v_max_f32_e32 v59, 0, v59
	v_max_f32_e32 v52, 0, v52
	v_max_f32_e32 v53, 0, v53
	v_max_f32_e32 v54, 0, v54
	v_max_f32_e32 v55, 0, v55
	v_max_f32_e32 v48, 0, v48
	v_max_f32_e32 v49, 0, v49
	v_max_f32_e32 v50, 0, v50
	v_max_f32_e32 v51, 0, v51
	v_max_f32_e32 v44, 0, v44
	v_max_f32_e32 v45, 0, v45
	v_max_f32_e32 v46, 0, v46
	v_max_f32_e32 v47, 0, v47
	v_max_f32_e32 v40, 0, v40
	v_max_f32_e32 v41, 0, v41
	v_max_f32_e32 v42, 0, v42
	v_max_f32_e32 v43, 0, v43
	v_max_f32_e32 v36, 0, v36
	v_max_f32_e32 v37, 0, v37
	v_max_f32_e32 v38, 0, v38
	v_max_f32_e32 v39, 0, v39
	v_max_f32_e32 v32, 0, v32
	v_max_f32_e32 v33, 0, v33
	v_max_f32_e32 v34, 0, v34
	v_max_f32_e32 v35, 0, v35
	v_max_f32_e32 v28, 0, v28
	v_max_f32_e32 v29, 0, v29
	v_max_f32_e32 v30, 0, v30
	v_max_f32_e32 v31, 0, v31
	v_max_f32_e32 v24, 0, v24
	v_max_f32_e32 v25, 0, v25
	v_max_f32_e32 v26, 0, v26
	v_max_f32_e32 v27, 0, v27
	v_max_f32_e32 v20, 0, v20
	v_max_f32_e32 v21, 0, v21
	v_max_f32_e32 v22, 0, v22
	v_max_f32_e32 v23, 0, v23
	v_max_f32_e32 v16, 0, v16
	v_max_f32_e32 v17, 0, v17
	v_max_f32_e32 v18, 0, v18
	v_max_f32_e32 v19, 0, v19
	v_max_f32_e32 v12, 0, v12
	v_max_f32_e32 v13, 0, v13
	v_max_f32_e32 v14, 0, v14
	v_max_f32_e32 v15, 0, v15
	v_max_f32_e32 v8, 0, v8
	v_max_f32_e32 v9, 0, v9
	v_max_f32_e32 v10, 0, v10
	v_max_f32_e32 v11, 0, v11
	v_max_f32_e32 v4, 0, v4
	v_max_f32_e32 v5, 0, v5
	v_max_f32_e32 v6, 0, v6
	v_max_f32_e32 v7, 0, v7
	v_max_f32_e32 v0, 0, v0
	v_max_f32_e32 v1, 0, v1
	v_max_f32_e32 v2, 0, v2
	v_max_f32_e32 v3, 0, v3
	v_lshlrev_b64 v[124:125], 13, v[128:129]
	v_pk_mul_f32 v[116:117], v[116:117], v[116:117]
	v_pk_mul_f32 v[118:119], v[118:119], v[118:119]
	v_pk_mul_f32 v[112:113], v[112:113], v[112:113]
	v_pk_mul_f32 v[114:115], v[114:115], v[114:115]
	v_pk_mul_f32 v[108:109], v[108:109], v[108:109]
	v_pk_mul_f32 v[110:111], v[110:111], v[110:111]
	v_pk_mul_f32 v[104:105], v[104:105], v[104:105]
	v_pk_mul_f32 v[106:107], v[106:107], v[106:107]
	v_pk_mul_f32 v[100:101], v[100:101], v[100:101]
	v_pk_mul_f32 v[102:103], v[102:103], v[102:103]
	v_lshlrev_b64 v[88:89], 13, v[88:89]
	v_pk_mul_f32 v[84:85], v[84:85], v[84:85]
	v_pk_mul_f32 v[86:87], v[86:87], v[86:87]
	v_pk_mul_f32 v[80:81], v[80:81], v[80:81]
	v_pk_mul_f32 v[82:83], v[82:83], v[82:83]
	v_pk_mul_f32 v[76:77], v[76:77], v[76:77]
	v_pk_mul_f32 v[78:79], v[78:79], v[78:79]
	v_pk_mul_f32 v[72:73], v[72:73], v[72:73]
	v_pk_mul_f32 v[74:75], v[74:75], v[74:75]
	v_pk_mul_f32 v[68:69], v[68:69], v[68:69]
	v_pk_mul_f32 v[70:71], v[70:71], v[70:71]
	v_pk_mul_f32 v[64:65], v[64:65], v[64:65]
	v_pk_mul_f32 v[66:67], v[66:67], v[66:67]
	v_pk_mul_f32 v[60:61], v[60:61], v[60:61]
	v_pk_mul_f32 v[62:63], v[62:63], v[62:63]
	v_pk_mul_f32 v[56:57], v[56:57], v[56:57]
	v_pk_mul_f32 v[58:59], v[58:59], v[58:59]
	v_pk_mul_f32 v[52:53], v[52:53], v[52:53]
	v_pk_mul_f32 v[54:55], v[54:55], v[54:55]
	v_pk_mul_f32 v[48:49], v[48:49], v[48:49]
	v_pk_mul_f32 v[50:51], v[50:51], v[50:51]
	v_pk_mul_f32 v[44:45], v[44:45], v[44:45]
	v_pk_mul_f32 v[46:47], v[46:47], v[46:47]
; DI int tidx() { int t = threadIdx.x; asm volatile("" : "+v"(t)); return t; }
; DI int bidx() { int b = blockIdx.x; asm volatile("" : "+s"(b)); return b; }
;     ...
;   P8STAGE_B(P8SB(0, 0), 0, 0); P8STAGE_A(P8SA(0, 0), 0, 0);
;   P8STAGE_B(P8SB(0, 1), 1, 0); P8STAGE_A(P8SA(0, 1), 1, 0);
; template <bool RELU2>
; DI void phase_gemm_plain(const bf16_t* X, int K, const bf16_t* W, int N, bf16_t* out, char* lds) {
;     ...
;   for (int it = bidx(); it < 128 * ntn; it += gridDim.x) {
;     int mt = it / ntn, nt = it % ntn;
;     if (ntn == 4) {
;       const int r = it >> 8, w = it & 255, x = w & 7, slot = w >> 3;
;       mt = 16 * x + (r & 1) * 8 + (slot >> 2); nt = slot & 3;
;     }
;     acc8_t acc;
; #pragma unroll
;     for (int a = 0; a < 2; ++a)
; #pragma unroll
;       for (int b = 0; b < 2; ++b)
; #pragma unroll
;         for (int m = 0; m < 4; ++m)
; #pragma unroll
;           for (int q = 0; q < 2; ++q) acc[a][b][m][q] = f32x4v{0.f, 0.f, 0.f, 0.f};
;     asm volatile("s_waitcnt vmcnt(0)" ::: "memory");
;     gemm_main8(acc, W + (size_t)nt * 256 * K, K, X + (size_t)mt * 256 * K, K, K / 64, lds);
;     const int lane = tidx() & 63, wid = tidx() >> 6, wr = wid >> 2, wc = wid & 3, fr = lane & 15, fq = lane >> 4;
; #pragma unroll
;     for (int ai = 0; ai < 2; ++ai)
; #pragma unroll
;       for (int bj = 0; bj < 2; ++bj)
; #pragma unroll
;         for (int m = 0; m < 4; ++m)
; #pragma unroll
;           for (int q = 0; q < 2; ++q) {
;             float a = acc[ai][bj][m][q][0], b = acc[ai][bj][m][q][1], c = acc[ai][bj][m][q][2], d = acc[ai][bj][m][q][3];
;             if (RELU2) { a = fmaxf(a, 0.f); a *= a; b = fmaxf(b, 0.f); b *= b; c = fmaxf(c, 0.f); c *= c; d = fmaxf(d, 0.f); d *= d; }
;             const int tok = mt * 256 + bj * 128 + wc * 32 + q * 16 + fr, n = nt * 256 + ai * 128 + wr * 64 + m * 16 + fq * 4;
;             store_bf4(out + (size_t)tok * N + n, a, b, c, d);
;           }
	v_pk_mul_f32 v[40:41], v[40:41], v[40:41]
	v_pk_mul_f32 v[42:43], v[42:43], v[42:43]
	v_pk_mul_f32 v[36:37], v[36:37], v[36:37]
	v_pk_mul_f32 v[38:39], v[38:39], v[38:39]
	v_pk_mul_f32 v[32:33], v[32:33], v[32:33]
	v_pk_mul_f32 v[34:35], v[34:35], v[34:35]
	v_pk_mul_f32 v[28:29], v[28:29], v[28:29]
	v_pk_mul_f32 v[30:31], v[30:31], v[30:31]
	v_pk_mul_f32 v[24:25], v[24:25], v[24:25]
	v_pk_mul_f32 v[26:27], v[26:27], v[26:27]
	v_pk_mul_f32 v[20:21], v[20:21], v[20:21]
	v_pk_mul_f32 v[22:23], v[22:23], v[22:23]
	v_pk_mul_f32 v[16:17], v[16:17], v[16:17]
	v_pk_mul_f32 v[18:19], v[18:19], v[18:19]
	v_pk_mul_f32 v[12:13], v[12:13], v[12:13]
	v_pk_mul_f32 v[14:15], v[14:15], v[14:15]
	v_pk_mul_f32 v[8:9], v[8:9], v[8:9]
	v_pk_mul_f32 v[10:11], v[10:11], v[10:11]
	v_pk_mul_f32 v[4:5], v[4:5], v[4:5]
	v_pk_mul_f32 v[6:7], v[6:7], v[6:7]
	v_pk_mul_f32 v[0:1], v[0:1], v[0:1]
	v_pk_mul_f32 v[2:3], v[2:3], v[2:3]
	s_add_i32 s0, s0, s16
	v_lshl_add_u64 v[124:125], v[130:131], 0, v[124:125]
	v_cvt_pk_bf16_f32 v126, v126, v127
	v_cvt_pk_bf16_f32 v127, v122, v123
	v_cvt_pk_bf16_f32 v116, v116, v117
	v_cvt_pk_bf16_f32 v117, v118, v119
	v_cvt_pk_bf16_f32 v112, v112, v113
	v_cvt_pk_bf16_f32 v113, v114, v115
	v_cvt_pk_bf16_f32 v108, v108, v109
	v_cvt_pk_bf16_f32 v109, v110, v111
	v_cvt_pk_bf16_f32 v104, v104, v105
	v_cvt_pk_bf16_f32 v105, v106, v107
	v_cvt_pk_bf16_f32 v100, v100, v101
	v_cvt_pk_bf16_f32 v101, v102, v103
	v_lshl_add_u64 v[92:93], v[130:131], 0, v[92:93]
	v_cvt_pk_bf16_f32 v96, v98, v99
	v_lshl_add_u64 v[88:89], v[130:131], 0, v[88:89]
	v_cvt_pk_bf16_f32 v94, v94, v95
	v_cvt_pk_bf16_f32 v95, v90, v91
	v_cvt_pk_bf16_f32 v84, v84, v85
	v_cvt_pk_bf16_f32 v85, v86, v87
	v_cvt_pk_bf16_f32 v80, v80, v81
	v_cvt_pk_bf16_f32 v81, v82, v83
	v_cvt_pk_bf16_f32 v76, v76, v77
	v_cvt_pk_bf16_f32 v77, v78, v79
	v_cvt_pk_bf16_f32 v72, v72, v73
	v_cvt_pk_bf16_f32 v73, v74, v75
	v_cvt_pk_bf16_f32 v68, v68, v69
	v_cvt_pk_bf16_f32 v69, v70, v71
	v_cvt_pk_bf16_f32 v64, v64, v65
	v_cvt_pk_bf16_f32 v65, v66, v67
	v_cvt_pk_bf16_f32 v60, v60, v61
	v_cvt_pk_bf16_f32 v61, v62, v63
	v_cvt_pk_bf16_f32 v56, v56, v57
	v_cvt_pk_bf16_f32 v57, v58, v59
	v_cvt_pk_bf16_f32 v52, v52, v53
	v_cvt_pk_bf16_f32 v53, v54, v55
	v_cvt_pk_bf16_f32 v48, v48, v49
	v_cvt_pk_bf16_f32 v49, v50, v51
	v_cvt_pk_bf16_f32 v44, v44, v45
	v_cvt_pk_bf16_f32 v45, v46, v47
	v_cvt_pk_bf16_f32 v40, v40, v41
	v_cvt_pk_bf16_f32 v41, v42, v43
	v_cvt_pk_bf16_f32 v36, v36, v37
	v_cvt_pk_bf16_f32 v37, v38, v39
	v_cvt_pk_bf16_f32 v32, v32, v33
	v_cvt_pk_bf16_f32 v33, v34, v35
	v_cvt_pk_bf16_f32 v28, v28, v29
	v_cvt_pk_bf16_f32 v29, v30, v31
	v_cvt_pk_bf16_f32 v24, v24, v25
	v_cvt_pk_bf16_f32 v25, v26, v27
	v_cvt_pk_bf16_f32 v20, v20, v21
	v_cvt_pk_bf16_f32 v21, v22, v23
	v_cvt_pk_bf16_f32 v16, v16, v17
	v_cvt_pk_bf16_f32 v17, v18, v19
	v_cvt_pk_bf16_f32 v12, v12, v13
	v_cvt_pk_bf16_f32 v13, v14, v15
	v_cvt_pk_bf16_f32 v8, v8, v9
	v_cvt_pk_bf16_f32 v9, v10, v11
	v_cvt_pk_bf16_f32 v4, v4, v5
	v_cvt_pk_bf16_f32 v5, v6, v7
	v_cvt_pk_bf16_f32 v0, v0, v1
	v_cvt_pk_bf16_f32 v1, v2, v3
	s_cmpk_lt_i32 s0, 0x800
	ds_write_b64 v190, v[132:133]
	ds_write_b64 v191, v[126:127]
	ds_write_b64 v190, v[116:117] offset:32
	ds_write_b64 v191, v[112:113] offset:32
	ds_write_b64 v190, v[108:109] offset:64
	ds_write_b64 v191, v[104:105] offset:64
	ds_write_b64 v190, v[100:101] offset:96
	ds_write_b64 v192, v[96:97]
	ds_write_b64 v193, v[94:95]
	ds_write_b64 v192, v[84:85] offset:32
	ds_write_b64 v193, v[80:81] offset:32
	ds_write_b64 v192, v[76:77] offset:64
	ds_write_b64 v193, v[72:73] offset:64
	ds_write_b64 v192, v[68:69] offset:96
	ds_write_b64 v193, v[64:65] offset:96
	ds_write_b64 v190, v[60:61] offset:256
	ds_write_b64 v191, v[56:57] offset:256
	ds_write_b64 v190, v[52:53] offset:288
	ds_write_b64 v191, v[48:49] offset:288
	ds_write_b64 v190, v[44:45] offset:320
	ds_write_b64 v191, v[40:41] offset:320
	ds_write_b64 v190, v[36:37] offset:352
	ds_write_b64 v191, v[32:33] offset:352
	ds_write_b64 v192, v[28:29] offset:256
	ds_write_b64 v193, v[24:25] offset:256
	ds_write_b64 v192, v[20:21] offset:288
	ds_write_b64 v193, v[16:17] offset:288
	ds_write_b64 v192, v[12:13] offset:320
	ds_write_b64 v193, v[8:9] offset:320
	ds_write_b64 v192, v[4:5] offset:352
	ds_write_b64 v193, v[0:1] offset:352
	s_waitcnt lgkmcnt(0)
	s_barrier
	ds_read_b128 v[0:3], v194
	ds_read_b128 v[4:7], v194 offset:1056
	ds_read_b128 v[8:11], v194 offset:2112
	ds_read_b128 v[12:15], v194 offset:3168
	ds_read_b128 v[16:19], v194 offset:4224
	ds_read_b128 v[20:23], v194 offset:5280
	ds_read_b128 v[24:27], v194 offset:6336
	ds_read_b128 v[28:31], v194 offset:7392
	ds_read_b128 v[32:35], v194 offset:8448
	ds_read_b128 v[36:39], v194 offset:9504
	ds_read_b128 v[40:43], v194 offset:10560
	ds_read_b128 v[44:47], v194 offset:11616
	ds_read_b128 v[48:51], v194 offset:12672
	ds_read_b128 v[52:55], v194 offset:13728
	ds_read_b128 v[56:59], v194 offset:14784
	ds_read_b128 v[60:63], v194 offset:15840
	s_waitcnt lgkmcnt(0)
	s_barrier
	s_cselect_b32 s13, 1, 0
	s_mov_b32 s12, 0
	s_cmp_eq_u32 s13, 1
	s_cbranch_scc0 .Lpfff1_none
	s_and_b32 s12, s0, 15
	s_lshr_b32 s83, s0, 4
	s_lshl_b32 s12, s12, 19
	s_lshl_b32 s83, s83, 19
	s_add_u32 s56, s26, s83
	s_addc_u32 s57, s27, 0
	v_readlane_b32 s82, v254, 48
	v_readlane_b32 s83, v254, 49
	s_nop 3
	s_add_u32 s22, s82, s12
	s_addc_u32 s23, s83, 0
	v_readfirstlane_b32 s82, v162
	s_nop 3
	s_lshl_b32 s82, s82, 4
	v_lshl_add_u64 v[182:183], s[56:57], 0, v[152:153]
	v_lshl_add_u64 v[184:185], s[22:23], 0, v[152:153]
	s_add_i32 m0, s82, 0x10000
	s_nop 0
	global_load_lds_dwordx4 v152, s[56:57]
	s_add_i32 m0, s82, 0x12000
	v_lshl_add_u64 v[186:187], v[182:183], 0, s[44:45]
	global_load_lds_dwordx4 v[186:187], off
	s_mov_b32 m0, s82
	s_nop 0
	global_load_lds_dwordx4 v152, s[22:23]
	s_add_i32 m0, s82, 0x2000
	v_lshl_add_u64 v[186:187], v[184:185], 0, s[44:45]
	global_load_lds_dwordx4 v[186:187], off
	s_add_i32 m0, s82, 0x14000
	v_lshl_add_u64 v[186:187], v[182:183], 0, s[50:51]
	global_load_lds_dwordx4 v[186:187], off
	s_add_i32 m0, s82, 0x16000
	v_lshl_add_u64 v[186:187], v[182:183], 0, s[64:65]
	global_load_lds_dwordx4 v[186:187], off
	s_add_i32 m0, s82, 0x4000
	v_lshl_add_u64 v[186:187], v[184:185], 0, s[50:51]
	global_load_lds_dwordx4 v[186:187], off
	s_add_i32 m0, s82, 0x6000
	v_lshl_add_u64 v[186:187], v[184:185], 0, s[64:65]
	global_load_lds_dwordx4 v[186:187], off
	s_mov_b32 s12, 1
; DI int bidx() { int b = blockIdx.x; asm volatile("" : "+s"(b)); return b; }
; #define P8WV(n) asm volatile("s_waitcnt vmcnt(" #n ")" ::: "memory")
; #define P8BAR __builtin_amdgcn_s_barrier()
;     ...
;   P8STAGE_B(P8SB(0, 0), 0, 0); P8STAGE_A(P8SA(0, 0), 0, 0);
;   P8STAGE_B(P8SB(0, 1), 1, 0); P8STAGE_A(P8SA(0, 1), 1, 0);
;   if (wr == 1) P8BAR;
;   P8WV(4); P8BAR;
;   P8STAGE_B(P8SB(1, 0), 0, 1); P8STAGE_A(P8SA(1, 0), 0, 1); P8STAGE_B(P8SB(1, 1), 1, 1);
;   P8WV(6); P8BAR;
; template <bool RELU2>
; DI void phase_gemm_plain(const bf16_t* X, int K, const bf16_t* W, int N, bf16_t* out, char* lds) {
;     ...
;   for (int it = bidx(); it < 128 * ntn; it += gridDim.x) {
;     int mt = it / ntn, nt = it % ntn;
;     if (ntn == 4) {
;       const int r = it >> 8, w = it & 255, x = w & 7, slot = w >> 3;
;       mt = 16 * x + (r & 1) * 8 + (slot >> 2); nt = slot & 3;
;     }
;     acc8_t acc;
; #pragma unroll
;     for (int a = 0; a < 2; ++a)
; #pragma unroll
;       for (int b = 0; b < 2; ++b)
; #pragma unroll
;         for (int m = 0; m < 4; ++m)
; #pragma unroll
;           for (int q = 0; q < 2; ++q) acc[a][b][m][q] = f32x4v{0.f, 0.f, 0.f, 0.f};
;     asm volatile("s_waitcnt vmcnt(0)" ::: "memory");
;     gemm_main8(acc, W + (size_t)nt * 256 * K, K, X + (size_t)mt * 256 * K, K, K / 64, lds);
;     ...
;             store_bf4(out + (size_t)tok * N + n, a, b, c, d);
;           }
.Lpfff1_none:
	v_writelane_b32 v255, s12, 51
	s_cmp_eq_u32 s13, 1
	global_store_dwordx4 v[196:197], v[0:3], off
	v_lshl_add_u64 v[196:197], v[196:197], 0, s[24:25]
	global_store_dwordx4 v[196:197], v[4:7], off
	v_lshl_add_u64 v[196:197], v[196:197], 0, s[24:25]
	global_store_dwordx4 v[196:197], v[8:11], off
	v_lshl_add_u64 v[196:197], v[196:197], 0, s[24:25]
	global_store_dwordx4 v[196:197], v[12:15], off
	v_lshl_add_u64 v[196:197], v[196:197], 0, s[24:25]
	global_store_dwordx4 v[196:197], v[16:19], off
	v_lshl_add_u64 v[196:197], v[196:197], 0, s[24:25]
	global_store_dwordx4 v[196:197], v[20:23], off
	v_lshl_add_u64 v[196:197], v[196:197], 0, s[24:25]
	global_store_dwordx4 v[196:197], v[24:27], off
	v_lshl_add_u64 v[196:197], v[196:197], 0, s[24:25]
	global_store_dwordx4 v[196:197], v[28:31], off
	v_lshl_add_u64 v[196:197], v[196:197], 0, s[24:25]
	global_store_dwordx4 v[196:197], v[32:35], off
	v_lshl_add_u64 v[196:197], v[196:197], 0, s[24:25]
	global_store_dwordx4 v[196:197], v[36:39], off
	v_lshl_add_u64 v[196:197], v[196:197], 0, s[24:25]
	global_store_dwordx4 v[196:197], v[40:43], off
	v_lshl_add_u64 v[196:197], v[196:197], 0, s[24:25]
	global_store_dwordx4 v[196:197], v[44:47], off
	v_lshl_add_u64 v[196:197], v[196:197], 0, s[24:25]
	global_store_dwordx4 v[196:197], v[48:51], off
	v_lshl_add_u64 v[196:197], v[196:197], 0, s[24:25]
	global_store_dwordx4 v[196:197], v[52:55], off
	v_lshl_add_u64 v[196:197], v[196:197], 0, s[24:25]
	global_store_dwordx4 v[196:197], v[56:59], off
	v_lshl_add_u64 v[196:197], v[196:197], 0, s[24:25]
	global_store_dwordx4 v[196:197], v[60:63], off
	s_cbranch_scc0 .LBB0_337
.LBB0_350:
	v_mov_b32_e32 v3, v162
	v_readlane_b32 vcc_lo, v255, 51
	s_nop 4
	s_mov_b32 vcc_hi, 0
	s_mov_b64 vcc, vcc
	s_cbranch_vccnz .Lpfff1_w0a
	s_waitcnt vmcnt(0)
	s_branch .Lpfff1_w0b
.Lpfff1_w0a:
.Lpfff1_w0b:
	s_ashr_i32 s1, s0, 31
	v_ashrrev_i32_e32 v0, 31, v3
	v_lshrrev_b32_e32 v0, 26, v0
	v_add_u32_e32 v0, v3, v0
	v_ashrrev_i32_e32 v2, 6, v0
	v_bfe_i32 v0, v3, 27, 1
	v_lshlrev_b32_e32 v131, 4, v3
	v_lshrrev_b32_e32 v0, 22, v0
	v_add_u32_e32 v0, v131, v0
	v_and_b32_e32 v0, 0xfffffc00, v0
	v_sub_u32_e32 v0, v131, v0
	s_lshr_b32 s1, s1, 28
	v_lshrrev_b32_e32 v1, 4, v0
	s_add_i32 s1, s0, s1
	v_bitop3_b32 v1, v1, v0, 32 bitop3:0x6c
	v_ashrrev_i32_e32 v0, 31, v0
	s_ashr_i32 s80, s1, 4
	s_and_b32 s1, s1, -16
	v_lshrrev_b32_e32 v0, 26, v0
	s_sub_i32 s8, s0, s1
	v_lshlrev_b32_e32 v4, 3, v2
	v_add_u32_e32 v0, v1, v0
	s_ashr_i32 s9, s8, 31
	v_and_b32_e32 v6, 0x1ffff0, v4
	v_ashrrev_i32_e32 v4, 6, v0
	s_lshl_b64 s[24:25], s[8:9], 19
	v_readlane_b32 s1, v254, 48
	v_mul_i32_i24_e32 v5, 64, v4
	s_add_u32 s22, s1, s24
	v_readlane_b32 s1, v254, 49
	v_sub_u32_e32 v1, v1, v5
	s_addc_u32 s23, s1, s25
	s_ashr_i32 s81, s80, 31
	v_lshlrev_b32_e32 v0, 5, v2
	v_ashrrev_i16_sdwa v1, v175, sext(v1) dst_sel:DWORD dst_unused:UNUSED_PAD src0_sel:DWORD src1_sel:BYTE_0
	s_lshl_b64 s[82:83], s[80:81], 19
	v_and_b32_e32 v0, 32, v0
	v_bfe_i32 v5, v1, 0, 16
	s_add_u32 s56, s26, s82
	v_add_u32_e32 v0, v0, v5
	v_add_lshl_u32 v1, v4, v6, 11
	v_add_u32_e32 v133, 0x10000, v131
	s_addc_u32 s57, s27, s83
	v_lshl_add_u32 v152, v0, 1, v1
	v_readfirstlane_b32 s1, v133
	v_add_u32_e32 v135, 0x12000, v131
	v_lshl_add_u64 v[0:1], s[56:57], 0, v[152:153]
	s_mov_b32 m0, s1
	v_readlane_b32 vcc_lo, v255, 51
	s_nop 4
	s_mov_b32 vcc_hi, 0
	s_mov_b64 vcc, vcc
	v_readfirstlane_b32 s1, v135
	s_cbranch_vccnz .Lpfff1_s0
	global_load_lds_dwordx4 v152, s[56:57]
.Lpfff1_s0:
	v_lshl_add_u64 v[6:7], v[0:1], 0, s[44:45]
	s_mov_b32 m0, s1
	v_readfirstlane_b32 s1, v131
	v_add_u32_e32 v136, 0x2000, v131
	s_cbranch_vccnz .Lpfff1_s1
	global_load_lds_dwordx4 v[6:7], off
.Lpfff1_s1:
	v_lshl_add_u64 v[128:129], s[22:23], 0, v[152:153]
	s_mov_b32 m0, s1
	v_readfirstlane_b32 s1, v136
	v_add_u32_e32 v137, 0x14000, v131
	s_cbranch_vccnz .Lpfff1_s2
	global_load_lds_dwordx4 v152, s[22:23]
.Lpfff1_s2:
	v_lshl_add_u64 v[6:7], v[128:129], 0, s[44:45]
	s_mov_b32 m0, s1
	v_readfirstlane_b32 s1, v137
	v_add_u32_e32 v138, 0x16000, v131
	s_cbranch_vccnz .Lpfff1_s3
	global_load_lds_dwordx4 v[6:7], off
.Lpfff1_s3:
	v_lshl_add_u64 v[6:7], v[0:1], 0, s[50:51]
	s_mov_b32 m0, s1
	v_readfirstlane_b32 s1, v138
	v_add_u32_e32 v139, 0x4000, v131
	s_cbranch_vccnz .Lpfff1_s4
	global_load_lds_dwordx4 v[6:7], off
.Lpfff1_s4:
	v_lshl_add_u64 v[6:7], v[0:1], 0, s[64:65]
	s_mov_b32 m0, s1
	v_readfirstlane_b32 s1, v139
	v_add_u32_e32 v140, 0x6000, v131
	s_cbranch_vccnz .Lpfff1_s5
	global_load_lds_dwordx4 v[6:7], off
.Lpfff1_s5:
	v_lshl_add_u64 v[6:7], v[128:129], 0, s[50:51]
	s_mov_b32 m0, s1
	v_readfirstlane_b32 s1, v140
	s_cbranch_vccnz .Lpfff1_s6
	global_load_lds_dwordx4 v[6:7], off
.Lpfff1_s6:
	v_lshl_add_u64 v[6:7], v[128:129], 0, s[64:65]
	s_mov_b32 m0, s1
	v_readfirstlane_b32 s1, v3
	s_cbranch_vccnz .Lpfff1_s7
	global_load_lds_dwordx4 v[6:7], off
.Lpfff1_s7:
	s_ashr_i32 s9, s1, 8
	s_cmp_lg_u32 s9, 1
	s_cbranch_scc1 .LBB0_352
	s_barrier
.LBB0_352:
	v_add_u32_e32 v141, 0x18000, v131
	v_add_u32_e32 v142, 0x1a000, v131
	v_readfirstlane_b32 s12, v141
	v_lshl_add_u64 v[6:7], v[0:1], 0, s[66:67]
	s_mov_b32 m0, s12
	s_mov_b64 s[22:23], 0x20080
	v_readfirstlane_b32 s12, v142
	v_add_u32_e32 v143, 0x8000, v131
	v_readlane_b32 vcc_lo, v255, 51
	s_nop 4
	s_mov_b32 vcc_hi, 0
	s_mov_b64 vcc, vcc
	s_cbranch_vccnz .Lpfff1_w1a
	s_waitcnt vmcnt(4)
	s_branch .Lpfff1_w1b
; #define P8WV(n) asm volatile("s_waitcnt vmcnt(" #n ")" ::: "memory")
; #define P8BAR __builtin_amdgcn_s_barrier()
;     ...
;   P8STAGE_B(P8SB(1, 0), 0, 1); P8STAGE_A(P8SA(1, 0), 0, 1); P8STAGE_B(P8SB(1, 1), 1, 1);
;   P8WV(6); P8BAR;
; template <bool RELU2>
; DI void phase_gemm_plain(const bf16_t* X, int K, const bf16_t* W, int N, bf16_t* out, char* lds) {
;     ...
;     acc8_t acc;
; #pragma unroll
;     for (int a = 0; a < 2; ++a)
; #pragma unroll
;       for (int b = 0; b < 2; ++b)
; #pragma unroll
;         for (int m = 0; m < 4; ++m)
; #pragma unroll
;           for (int q = 0; q < 2; ++q) acc[a][b][m][q] = f32x4v{0.f, 0.f, 0.f, 0.f};
.Lpfff1_w1a:
	s_waitcnt vmcnt(20)
.Lpfff1_w1b:
	s_barrier
	global_load_lds_dwordx4 v[6:7], off
	v_lshl_add_u64 v[6:7], v[0:1], 0, s[22:23]
	s_mov_b32 m0, s12
	v_readfirstlane_b32 s12, v143
	v_add_u32_e32 v144, 0xa000, v131
	global_load_lds_dwordx4 v[6:7], off
	v_lshl_add_u64 v[6:7], v[128:129], 0, s[66:67]
	s_mov_b32 m0, s12
	v_readfirstlane_b32 s12, v144
	v_add_u32_e32 v145, 0x1c000, v131
	global_load_lds_dwordx4 v[6:7], off
	v_lshl_add_u64 v[6:7], v[128:129], 0, s[22:23]
	s_mov_b32 m0, s12
	v_readfirstlane_b32 s12, v145
	v_add_u32_e32 v147, 0x1e000, v131
	global_load_lds_dwordx4 v[6:7], off
	v_lshl_add_u64 v[6:7], v[0:1], 0, s[38:39]
	s_mov_b32 m0, s12
	v_readfirstlane_b32 s12, v147
	global_load_lds_dwordx4 v[6:7], off
	v_lshl_add_u64 v[0:1], v[0:1], 0, s[52:53]
	s_mov_b32 m0, s12
	v_and_b32_e32 v8, 15, v3
	global_load_lds_dwordx4 v[0:1], off
	v_lshlrev_b32_e32 v6, 2, v3
	v_and_b32_e32 v9, 48, v3
	v_lshlrev_b32_e32 v0, 6, v8
	v_and_b32_e32 v6, 32, v6
	v_or_b32_e32 v1, v0, v9
	v_bitop3_b32 v7, v0, v6, v9 bitop3:0x36
	v_lshlrev_b32_e32 v0, 6, v3
	v_and_b32_e32 v0, 0x3c0, v0
	s_lshl_b32 s12, s1, 6
	s_lshl_b32 s13, s9, 13
	v_bitop3_b32 v148, v0, v6, v9 bitop3:0x36
	v_lshlrev_b32_e32 v0, 14, v2
	s_and_b32 s12, s12, 0x3000
	s_or_b32 s9, s13, 0x800
	s_or_b32 s21, s13, 0x1000
	s_or_b32 s22, s13, 0x1800
	v_and_b32_e32 v0, 0xffff8000, v0
	v_lshl_add_u32 v0, v4, 11, v0
	v_and_b32_e32 v2, 1, v2
	s_add_u32 s24, s10, s24
	v_readlane_b32 vcc_lo, v255, 51
	s_nop 4
	s_mov_b32 vcc_hi, 0
	s_mov_b64 vcc, vcc
	s_cbranch_vccnz .Lpfff1_w2a
	s_waitcnt vmcnt(6)
	s_branch .Lpfff1_w2b
.Lpfff1_w2a:
	s_waitcnt vmcnt(22)
.Lpfff1_w2b:
	v_lshl_or_b32 v0, v2, 6, v0
	s_addc_u32 s25, s11, s25
	v_bitop3_b32 v8, v1, s33, v6 bitop3:0xde
	v_bitop3_b32 v10, v1, s62, v6 bitop3:0xde
	v_bitop3_b32 v11, v1, s63, v6 bitop3:0xde
	v_bitop3_b32 v1, v1, s28, v6 bitop3:0xde
	v_lshl_add_u32 v152, v5, 1, v0
	s_add_u32 s82, s10, s82
	v_mov_b32_e32 v0, 0
	s_addc_u32 s83, s11, s83
	s_mov_b32 s23, -2
	v_add_u32_e32 v149, s12, v8
	v_add_u32_e32 v130, s13, v7
	v_add_u32_e32 v146, s12, v10
	v_add_u32_e32 v134, s12, v11
	v_add_u32_e32 v132, s12, v1
	v_mov_b32_e32 v1, v0
	v_mov_b32_e32 v2, v0
	v_mov_b32_e32 v3, v0
	v_mov_b32_e32 v4, v0
	v_mov_b32_e32 v5, v0
	v_mov_b32_e32 v6, v0
	v_mov_b32_e32 v7, v0
	v_mov_b32_e32 v8, v0
	v_mov_b32_e32 v9, v0
	v_mov_b32_e32 v10, v0
	v_mov_b32_e32 v11, v0
	v_mov_b32_e32 v12, v0
	v_mov_b32_e32 v13, v0
	v_mov_b32_e32 v14, v0
	v_mov_b32_e32 v15, v0
	v_mov_b32_e32 v16, v0
	v_mov_b32_e32 v17, v0
	v_mov_b32_e32 v18, v0
	v_mov_b32_e32 v19, v0
	v_mov_b32_e32 v20, v0
	v_mov_b32_e32 v21, v0
	v_mov_b32_e32 v22, v0
	v_mov_b32_e32 v23, v0
	v_mov_b32_e32 v24, v0
	v_mov_b32_e32 v25, v0
	v_mov_b32_e32 v26, v0
	v_mov_b32_e32 v27, v0
	v_mov_b32_e32 v28, v0
	v_mov_b32_e32 v29, v0
	v_mov_b32_e32 v30, v0
	v_mov_b32_e32 v31, v0
	v_mov_b32_e32 v32, v0
	v_mov_b32_e32 v33, v0
	v_mov_b32_e32 v34, v0
	v_mov_b32_e32 v35, v0
	v_mov_b32_e32 v36, v0
	v_mov_b32_e32 v37, v0
	v_mov_b32_e32 v38, v0
	v_mov_b32_e32 v39, v0
	v_mov_b32_e32 v40, v0
	v_mov_b32_e32 v41, v0
	v_mov_b32_e32 v42, v0
	v_mov_b32_e32 v43, v0
	v_mov_b32_e32 v44, v0
	v_mov_b32_e32 v45, v0
	v_mov_b32_e32 v46, v0
	v_mov_b32_e32 v47, v0
	v_mov_b32_e32 v48, v0
	v_mov_b32_e32 v49, v0
	v_mov_b32_e32 v50, v0
	v_mov_b32_e32 v51, v0
	v_mov_b32_e32 v52, v0
	v_mov_b32_e32 v53, v0
	v_mov_b32_e32 v54, v0
	v_mov_b32_e32 v55, v0
	v_mov_b32_e32 v56, v0
	v_mov_b32_e32 v57, v0
	v_mov_b32_e32 v58, v0
	v_mov_b32_e32 v59, v0
	v_mov_b32_e32 v60, v0
	v_mov_b32_e32 v61, v0
	v_mov_b32_e32 v62, v0
	v_mov_b32_e32 v63, v0
	v_mov_b32_e32 v64, v0
	v_mov_b32_e32 v65, v0
	v_mov_b32_e32 v66, v0
	v_mov_b32_e32 v67, v0
	v_mov_b32_e32 v68, v0
	v_mov_b32_e32 v69, v0
	v_mov_b32_e32 v70, v0
	v_mov_b32_e32 v71, v0
	v_mov_b32_e32 v72, v0
	v_mov_b32_e32 v73, v0
	v_mov_b32_e32 v74, v0
	v_mov_b32_e32 v75, v0
	v_mov_b32_e32 v76, v0
	v_mov_b32_e32 v77, v0
	v_mov_b32_e32 v78, v0
	v_mov_b32_e32 v79, v0
	v_mov_b32_e32 v80, v0
	v_mov_b32_e32 v81, v0
	v_mov_b32_e32 v82, v0
	v_mov_b32_e32 v83, v0
	v_mov_b32_e32 v84, v0
	v_mov_b32_e32 v85, v0
	v_mov_b32_e32 v86, v0
	v_mov_b32_e32 v87, v0
	v_mov_b32_e32 v88, v0
	v_mov_b32_e32 v89, v0
	v_mov_b32_e32 v90, v0
	v_mov_b32_e32 v91, v0
	v_mov_b32_e32 v92, v0
	v_mov_b32_e32 v93, v0
	v_mov_b32_e32 v94, v0
	v_mov_b32_e32 v95, v0
	v_mov_b32_e32 v96, v0
	v_mov_b32_e32 v97, v0
	v_mov_b32_e32 v98, v0
	v_mov_b32_e32 v99, v0
	v_mov_b32_e32 v100, v0
	v_mov_b32_e32 v101, v0
	v_mov_b32_e32 v102, v0
	v_mov_b32_e32 v103, v0
	v_mov_b32_e32 v104, v0
	v_mov_b32_e32 v105, v0
	v_mov_b32_e32 v106, v0
	v_mov_b32_e32 v107, v0
	v_mov_b32_e32 v108, v0
	v_mov_b32_e32 v109, v0
	v_mov_b32_e32 v110, v0
	v_mov_b32_e32 v111, v0
	v_mov_b32_e32 v112, v0
	v_mov_b32_e32 v113, v0
	v_mov_b32_e32 v114, v0
	v_mov_b32_e32 v115, v0
	v_mov_b32_e32 v116, v0
	v_mov_b32_e32 v117, v0
	v_mov_b32_e32 v118, v0
	v_mov_b32_e32 v119, v0
	v_mov_b32_e32 v120, v0
	v_mov_b32_e32 v121, v0
	v_mov_b32_e32 v122, v0
	v_mov_b32_e32 v123, v0
	v_mov_b32_e32 v124, v0
	v_mov_b32_e32 v125, v0
	v_mov_b32_e32 v126, v0
	v_mov_b32_e32 v127, v0
	s_barrier
